# grid-barrier spin loops poll without s_sleep (from v37)
# baseline (speedup 1.0000x reference)
; __device__ __forceinline__ unsigned xb_ld(unsigned* p)              { return __hip_atomic_load(p, __ATOMIC_RELAXED, __HIP_MEMORY_SCOPE_AGENT); }
; __device__ __forceinline__ unsigned xb_add(unsigned* p, unsigned v) { return __hip_atomic_fetch_add(p, v, __ATOMIC_RELAXED, __HIP_MEMORY_SCOPE_AGENT); }
; #define XB_SPIN(cond, bar) do { unsigned _sp = 0; while (cond) { __builtin_amdgcn_s_sleep(1); \
;     if ((++_sp & 255u) == 0u) { if (xb_ld(&(bar)[XB_TMO])) break; if (_sp > XB_SPIN_CAP) { atomicAdd(&(bar)[XB_TMO], 1u); break; } } } } while (0)
; __device__ __forceinline__ void xcd_barrier(const XcdBarrier& b) {
;     ...
;             else XB_SPIN(xb_ld(&bar[XB_TOPGEN]) == tg, bar);
;             __builtin_amdgcn_fence(__ATOMIC_ACQUIRE, "agent");
;             xb_add(&bar[XB_XGEN(b.x)], 1u);
;             asm volatile("s_waitcnt vmcnt(0)" ::: "memory");
;         } else {
;             XB_SPIN(xb_ld(&bar[XB_XGEN(b.x)]) == gen, bar);
.LBB0_968:
	s_and_b32 s18, s22, 0xff
	s_mov_b64 s[16:17], -1
	s_cmp_lg_u32 s18, 0
	s_mov_b64 s[20:21], -1
	s_nop 0
	s_cbranch_scc0 .LBB0_971
	s_and_b64 vcc, exec, s[20:21]
	s_cbranch_vccz .LBB0_967
